# scan P2 waves: all four decay-prefix blocks requested together with the iteration's first LDS reads (separate registers) instead of one block per round trip
# baseline (speedup 1.0000x reference)
; #define LAS __attribute__((address_space(3)))
; __device__ __forceinline__ void scan_phase(LAS unsigned char* lds, const bf16_t* R, const bf16_t* Kb, const bf16_t* V, const bf16_t* WA, const float* k_k, const float* k_a, bf16_t* Y, int G, int bid, int tid) {
;     ...
;                 LAS unsigned char* buf = lds + (it & 1) * CK_BUF;
;                 const LAS unsigned char* ldp = lds + CK_LD + (it & 1) * 4096 + 16 * pj;
;                 const LAS unsigned char* stp = lds + CK_STG + (it & 1) * CK_STG_SZ + (pt * 64 + 4 * pj) * 4;
;                 f32x4 nkk = *(const LAS f32x4*)(stp), be = *(const LAS f32x4*)(stp + 4096), kp = *(const LAS f32x4*)(stp + 8192), rf = *(const LAS f32x4*)(stp + 12288), lf = *(const LAS f32x4*)(ldp + pt * 256);
;                 unsigned vsave = *(const LAS unsigned*)(lds + CK_STG + (it & 1) * CK_STG_SZ + 16384 + (pt * 16 + pj) * 4);
;                 asm volatile("" : "+v"(nkk), "+v"(be), "+v"(kp), "+v"(rf), "+v"(lf), "+v"(vsave));
;                 f32x4 Gc = (f32x4){0.f, 0.f, 0.f, 0.f};
;                 const int w4 = 4 * wq;
; #pragma unroll
;                 for (int s4 = 0; s4 < 16; s4 += 4) {
;                     if (s4 <= w4) {
;                         f32x4 x0 = *(const LAS f32x4*)(ldp + (s4 + 0) * 256), x1 = *(const LAS f32x4*)(ldp + (s4 + 1) * 256), x2 = *(const LAS f32x4*)(ldp + (s4 + 2) * 256), x3 = *(const LAS f32x4*)(ldp + (s4 + 3) * 256);
;                         asm volatile("" : "+v"(x0), "+v"(x1), "+v"(x2), "+v"(x3));
;                         if (s4 < w4) Gc += (x0 + x1) + (x2 + x3);
;                         else { const f32x4 z4 = (f32x4){0.f, 0.f, 0.f, 0.f};
;                             Gc += (s4 + 0 <= pt) ? x0 : z4; Gc += (s4 + 1 <= pt) ? x1 : z4; Gc += (s4 + 2 <= pt) ? x2 : z4; Gc += (s4 + 3 <= pt) ? x3 : z4; }
;                     }
;                 }
.LBB0_921:
	s_cmp_ge_u32 s60, 0x7f8000
	s_cselect_b64 s[0:1], -1, 0
	s_or_b64 s[0:1], s[58:59], s[0:1]
	s_and_b64 vcc, exec, s[0:1]
	s_cbranch_vccnz .LBB0_949
	s_and_b32 s78, s62, 1
	s_mul_i32 s0, s78, 0x4400
	s_add_i32 s96, s0, 0
	v_lshl_add_u32 v73, s78, 12, v160
	v_add3_u32 v3, s96, v162, v102
	v_add3_u32 v1, s96, v161, v104
	v_add_u32_e32 v2, v73, v161
	ds_read_b32 v72, v3 offset:61440
	ds_read_b128 v[44:47], v2 offset:31744
	ds_read_b128 v[36:39], v1 offset:57344
	ds_read_b128 v[28:31], v1 offset:53248
	ds_read_b128 v[32:35], v1 offset:49152
	ds_read_b128 v[40:43], v1 offset:45056
	ds_read_b128 v[52:55], v73 offset:32512
	ds_read_b128 v[56:59], v73 offset:32256
	ds_read_b128 v[60:63], v73 offset:32000
	ds_read_b128 v[64:67], v73 offset:31744
	ds_read_b128 v[200:203], v73 offset:33536
	ds_read_b128 v[204:207], v73 offset:33280
	ds_read_b128 v[208:211], v73 offset:33024
	ds_read_b128 v[212:215], v73 offset:32768
	ds_read_b128 v[216:219], v73 offset:34560
	ds_read_b128 v[220:223], v73 offset:34304
	ds_read_b128 v[224:227], v73 offset:34048
	ds_read_b128 v[228:231], v73 offset:33792
	ds_read_b128 v[232:235], v73 offset:35584
	ds_read_b128 v[236:239], v73 offset:35328
	ds_read_b128 v[240:243], v73 offset:35072
	ds_read_b128 v[244:247], v73 offset:34816
	s_and_b64 vcc, exec, s[52:53]
	s_waitcnt lgkmcnt(0)
	s_cbranch_vccnz .LBB0_925
	s_andn2_b64 vcc, exec, s[82:83]
	s_cbranch_vccnz .LBB0_926
	v_pk_add_f32 v[2:3], v[66:67], v[62:63]
	v_pk_add_f32 v[48:49], v[64:65], v[60:61]
	v_pk_add_f32 v[50:51], v[58:59], v[54:55]
	v_pk_add_f32 v[68:69], v[56:57], v[52:53]
	v_pk_add_f32 v[2:3], v[2:3], v[50:51]
	v_pk_add_f32 v[48:49], v[48:49], v[68:69]
	v_pk_add_f32 v[50:51], v[2:3], 0 op_sel_hi:[1,0]
	v_pk_add_f32 v[48:49], v[48:49], 0 op_sel_hi:[1,0]
	s_cbranch_execz .LBB0_927
	s_branch .LBB0_928

; #define LAS __attribute__((address_space(3)))
; __device__ __forceinline__ void scan_phase(LAS unsigned char* lds, const bf16_t* R, const bf16_t* Kb, const bf16_t* V, const bf16_t* WA, const float* k_k, const float* k_a, bf16_t* Y, int G, int bid, int tid) {
;     ...
;                     if (s4 <= w4) {
;                         f32x4 x0 = *(const LAS f32x4*)(ldp + (s4 + 0) * 256), x1 = *(const LAS f32x4*)(ldp + (s4 + 1) * 256), x2 = *(const LAS f32x4*)(ldp + (s4 + 2) * 256), x3 = *(const LAS f32x4*)(ldp + (s4 + 3) * 256);
;                         asm volatile("" : "+v"(x0), "+v"(x1), "+v"(x2), "+v"(x3));
;                         if (s4 < w4) Gc += (x0 + x1) + (x2 + x3);
;                         else { const f32x4 z4 = (f32x4){0.f, 0.f, 0.f, 0.f};
;                             Gc += (s4 + 0 <= pt) ? x0 : z4; Gc += (s4 + 1 <= pt) ? x1 : z4; Gc += (s4 + 2 <= pt) ? x2 : z4; Gc += (s4 + 3 <= pt) ? x3 : z4; }
;                     }
.LBB0_931:
	s_andn2_b64 vcc, exec, s[86:87]
	s_mov_b64 s[0:1], -1
	s_cbranch_vccnz .LBB0_933
	v_cndmask_b32_e64 v3, v215, 0, s[14:15]
	v_cndmask_b32_e64 v2, v214, 0, s[14:15]
	v_cndmask_b32_e64 v69, v213, 0, s[14:15]
	v_cndmask_b32_e64 v68, v212, 0, s[14:15]
	v_pk_add_f32 v[68:69], v[48:49], v[68:69]
	v_pk_add_f32 v[2:3], v[50:51], v[2:3]
	v_cndmask_b32_e64 v71, 0, v209, s[16:17]
	v_cndmask_b32_e64 v70, 0, v208, s[16:17]
	v_cndmask_b32_e64 v75, 0, v211, s[16:17]
	v_cndmask_b32_e64 v74, 0, v210, s[16:17]
	v_pk_add_f32 v[2:3], v[74:75], v[2:3]
	v_pk_add_f32 v[68:69], v[70:71], v[68:69]
	v_cndmask_b32_e64 v71, v207, 0, s[18:19]
	v_cndmask_b32_e64 v70, v206, 0, s[18:19]
	v_cndmask_b32_e64 v75, v205, 0, s[18:19]
	v_cndmask_b32_e64 v74, v204, 0, s[18:19]
	v_pk_add_f32 v[68:69], v[74:75], v[68:69]
	v_pk_add_f32 v[2:3], v[70:71], v[2:3]
	v_cndmask_b32_e64 v75, v201, 0, s[20:21]
	v_cndmask_b32_e64 v74, v200, 0, s[20:21]
	v_cndmask_b32_e64 v71, v203, 0, s[20:21]
	v_cndmask_b32_e64 v70, v202, 0, s[20:21]
	v_pk_add_f32 v[70:71], v[70:71], v[2:3]
	v_pk_add_f32 v[68:69], v[74:75], v[68:69]
	s_mov_b64 s[0:1], 0
.LBB0_933:
	s_andn2_b64 vcc, exec, s[0:1]
	s_cbranch_vccnz .LBB0_935
	v_pk_add_f32 v[2:3], v[214:215], v[210:211]
	v_pk_add_f32 v[60:61], v[212:213], v[208:209]
	v_pk_add_f32 v[54:55], v[206:207], v[202:203]
	v_pk_add_f32 v[52:53], v[204:205], v[200:201]
	v_pk_add_f32 v[2:3], v[2:3], v[54:55]
	v_pk_add_f32 v[52:53], v[60:61], v[52:53]
	v_pk_add_f32 v[70:71], v[50:51], v[2:3]
	v_pk_add_f32 v[68:69], v[48:49], v[52:53]

; #define LAS __attribute__((address_space(3)))
; __device__ __forceinline__ void scan_phase(LAS unsigned char* lds, const bf16_t* R, const bf16_t* Kb, const bf16_t* V, const bf16_t* WA, const float* k_k, const float* k_a, bf16_t* Y, int G, int bid, int tid) {
;     ...
;                     if (s4 <= w4) {
;                         f32x4 x0 = *(const LAS f32x4*)(ldp + (s4 + 0) * 256), x1 = *(const LAS f32x4*)(ldp + (s4 + 1) * 256), x2 = *(const LAS f32x4*)(ldp + (s4 + 2) * 256), x3 = *(const LAS f32x4*)(ldp + (s4 + 3) * 256);
;                         asm volatile("" : "+v"(x0), "+v"(x1), "+v"(x2), "+v"(x3));
;                         if (s4 < w4) Gc += (x0 + x1) + (x2 + x3);
;                         else { const f32x4 z4 = (f32x4){0.f, 0.f, 0.f, 0.f};
;                             Gc += (s4 + 0 <= pt) ? x0 : z4; Gc += (s4 + 1 <= pt) ? x1 : z4; Gc += (s4 + 2 <= pt) ? x2 : z4; Gc += (s4 + 3 <= pt) ? x3 : z4; }
;                     }
.LBB0_936:
	s_andn2_b64 vcc, exec, s[90:91]
	s_mov_b64 s[0:1], -1
	s_cbranch_vccnz .LBB0_938
	v_cndmask_b32_e64 v3, v231, 0, s[22:23]
	v_cndmask_b32_e64 v2, v230, 0, s[22:23]
	v_cndmask_b32_e64 v69, v229, 0, s[22:23]
	v_cndmask_b32_e64 v68, v228, 0, s[22:23]
	v_pk_add_f32 v[68:69], v[48:49], v[68:69]
	v_pk_add_f32 v[2:3], v[50:51], v[2:3]
	v_cndmask_b32_e64 v71, 0, v225, s[24:25]
	v_cndmask_b32_e64 v70, 0, v224, s[24:25]
	v_cndmask_b32_e64 v75, 0, v227, s[24:25]
	v_cndmask_b32_e64 v74, 0, v226, s[24:25]
	v_pk_add_f32 v[2:3], v[74:75], v[2:3]
	v_pk_add_f32 v[68:69], v[70:71], v[68:69]
	v_cndmask_b32_e64 v71, v223, 0, s[26:27]
	v_cndmask_b32_e64 v70, v222, 0, s[26:27]
	v_cndmask_b32_e64 v75, v221, 0, s[26:27]
	v_cndmask_b32_e64 v74, v220, 0, s[26:27]
	v_pk_add_f32 v[68:69], v[74:75], v[68:69]
	v_pk_add_f32 v[2:3], v[70:71], v[2:3]
	v_cndmask_b32_e64 v75, v217, 0, s[28:29]
	v_cndmask_b32_e64 v74, v216, 0, s[28:29]
	v_cndmask_b32_e64 v71, v219, 0, s[28:29]
	v_cndmask_b32_e64 v70, v218, 0, s[28:29]
	v_pk_add_f32 v[70:71], v[70:71], v[2:3]
	v_pk_add_f32 v[68:69], v[74:75], v[68:69]
	s_mov_b64 s[0:1], 0
.LBB0_938:
	s_andn2_b64 vcc, exec, s[0:1]
	s_cbranch_vccnz .LBB0_940
	v_pk_add_f32 v[2:3], v[230:231], v[226:227]
	v_pk_add_f32 v[60:61], v[228:229], v[224:225]
	v_pk_add_f32 v[54:55], v[222:223], v[218:219]
	v_pk_add_f32 v[52:53], v[220:221], v[216:217]
	v_pk_add_f32 v[2:3], v[2:3], v[54:55]
	v_pk_add_f32 v[52:53], v[60:61], v[52:53]
	v_pk_add_f32 v[70:71], v[50:51], v[2:3]
	v_pk_add_f32 v[68:69], v[48:49], v[52:53]

; #define LAS __attribute__((address_space(3)))
; __device__ __forceinline__ void scan_phase(LAS unsigned char* lds, const bf16_t* R, const bf16_t* Kb, const bf16_t* V, const bf16_t* WA, const float* k_k, const float* k_a, bf16_t* Y, int G, int bid, int tid) {
;     ...
;                     if (s4 <= w4) {
;                         f32x4 x0 = *(const LAS f32x4*)(ldp + (s4 + 0) * 256), x1 = *(const LAS f32x4*)(ldp + (s4 + 1) * 256), x2 = *(const LAS f32x4*)(ldp + (s4 + 2) * 256), x3 = *(const LAS f32x4*)(ldp + (s4 + 3) * 256);
;                         asm volatile("" : "+v"(x0), "+v"(x1), "+v"(x2), "+v"(x3));
;                         if (s4 < w4) Gc += (x0 + x1) + (x2 + x3);
;                         else { const f32x4 z4 = (f32x4){0.f, 0.f, 0.f, 0.f};
;                             Gc += (s4 + 0 <= pt) ? x0 : z4; Gc += (s4 + 1 <= pt) ? x1 : z4; Gc += (s4 + 2 <= pt) ? x2 : z4; Gc += (s4 + 3 <= pt) ? x3 : z4; }
;                     }
.LBB0_941:
	s_andn2_b64 vcc, exec, s[94:95]
	s_mov_b64 s[0:1], -1
	s_cbranch_vccnz .LBB0_943
	v_cndmask_b32_e64 v3, v247, 0, s[30:31]
	v_cndmask_b32_e64 v2, v246, 0, s[30:31]
	v_cndmask_b32_e64 v69, v245, 0, s[30:31]
	v_cndmask_b32_e64 v68, v244, 0, s[30:31]
	v_pk_add_f32 v[68:69], v[48:49], v[68:69]
	v_pk_add_f32 v[2:3], v[50:51], v[2:3]
	v_cndmask_b32_e64 v71, 0, v241, s[34:35]
	v_cndmask_b32_e64 v70, 0, v240, s[34:35]
	v_cndmask_b32_e64 v75, 0, v243, s[34:35]
	v_cndmask_b32_e64 v74, 0, v242, s[34:35]
	v_pk_add_f32 v[2:3], v[74:75], v[2:3]
	v_pk_add_f32 v[68:69], v[70:71], v[68:69]
	v_cndmask_b32_e64 v71, v239, 0, s[36:37]
	v_cndmask_b32_e64 v70, v238, 0, s[36:37]
	v_cndmask_b32_e64 v75, v237, 0, s[36:37]
	v_cndmask_b32_e64 v74, v236, 0, s[36:37]
	v_pk_add_f32 v[68:69], v[74:75], v[68:69]
	v_pk_add_f32 v[2:3], v[70:71], v[2:3]
	v_cndmask_b32_e64 v75, 0, v233, s[2:3]
	v_cndmask_b32_e64 v74, 0, v232, s[2:3]
	v_cndmask_b32_e64 v71, 0, v235, s[2:3]
	v_cndmask_b32_e64 v70, 0, v234, s[2:3]
	v_pk_add_f32 v[70:71], v[70:71], v[2:3]
	v_pk_add_f32 v[68:69], v[74:75], v[68:69]
	s_mov_b64 s[0:1], 0
.LBB0_943:
	s_andn2_b64 vcc, exec, s[0:1]
	s_cbranch_vccnz .LBB0_945
	v_pk_add_f32 v[2:3], v[246:247], v[242:243]
	v_pk_add_f32 v[60:61], v[244:245], v[240:241]
	v_pk_add_f32 v[54:55], v[238:239], v[234:235]
	v_pk_add_f32 v[52:53], v[236:237], v[232:233]
	v_pk_add_f32 v[2:3], v[2:3], v[54:55]
	v_pk_add_f32 v[52:53], v[60:61], v[52:53]
	v_pk_add_f32 v[70:71], v[50:51], v[2:3]
	v_pk_add_f32 v[68:69], v[48:49], v[52:53]
